# P1 wave-0 bias DMA block moved behind the first MFMA pair of the first K-iteration (MFMA-shadow placement)
# baseline (speedup 1.0000x reference)
.LBB0_381:
.LBB0_383:
	s_add_u32 s39, s82, 0x100
	s_addc_u32 s67, s83, 0
	s_mov_b32 s94, -2
	s_mov_b64 vcc, 0
	v_lshl_add_u64 v[132:133], s[4:5], 0, v[168:169]
	ds_read_b128 v[134:137], v199
	ds_read_b128 v[138:141], v200
	ds_read_b128 v[142:145], v201
	ds_read_b128 v[146:149], v202
	ds_read_b128 v[150:153], v203
	ds_read_b128 v[174:177], v204
	ds_read_b128 v[178:181], v205
	ds_read_b128 v[182:185], v206
	s_add_u32 s24, s4, vcc_lo
	s_addc_u32 s25, s5, vcc_hi
	s_add_u32 s24, s24, 0x100
	s_addc_u32 s25, s25, 0
	s_add_u32 s82, s39, vcc_lo
	s_addc_u32 s83, s67, vcc_hi
	s_cmpk_eq_i32 vcc_lo, 0x700
	s_cselect_b32 s87, s29, s83
	s_cselect_b32 s86, s38, s82
	s_cselect_b32 s83, s34, s25
	s_cselect_b32 s82, s35, s24
	v_lshl_add_u64 v[154:155], v[132:133], 0, vcc
	v_lshl_add_u64 v[250:251], v[154:155], 0, s[48:49]
	s_add_i32 m0, s79, 0x8000
	s_mov_b64 s[24:25], 0x20080
	ds_read_b128 v[218:221], v207
	ds_read_b128 v[222:225], v207 offset:2048
	ds_read_b128 v[226:229], v208
	ds_read_b128 v[230:233], v208 offset:2048
	ds_read_b128 v[234:237], v207 offset:4096
	ds_read_b128 v[238:241], v207 offset:6144
	ds_read_b128 v[242:245], v208 offset:4096
	ds_read_b128 v[246:249], v208 offset:6144
	global_load_lds_dwordx4 v[250:251], off
	v_lshl_add_u64 v[250:251], v[154:155], 0, s[24:25]
	s_add_i32 m0, s79, 0xa000
	s_mov_b64 s[24:25], 0x60080
	global_load_lds_dwordx4 v[250:251], off
	v_lshl_add_u64 v[250:251], v[154:155], 0, s[50:51]
	s_add_i32 m0, s79, 0xc000
	v_lshl_add_u64 v[154:155], v[154:155], 0, s[24:25]
	global_load_lds_dwordx4 v[250:251], off
	s_add_i32 m0, s79, 0xe000
	s_nop 0
	global_load_lds_dwordx4 v[154:155], off
	s_waitcnt vmcnt(16)
	s_waitcnt lgkmcnt(0)
	s_barrier
	s_setprio 0
	v_mfma_f32_16x16x32_bf16 v[128:131], v[134:137], v[218:221], 0
	v_mfma_f32_16x16x32_bf16 v[128:131], v[138:141], v[226:229], v[128:131]
	s_cmp_lg_u32 s98, 0
	s_cbranch_scc1 .Lp1b_skip
	v_mbcnt_lo_u32_b32 v255, -1, 0
	v_mbcnt_hi_u32_b32 v255, -1, v255
	s_cmp_gt_i32 s96, 13
	s_cbranch_scc1 .Lp1b_gate
	s_lshl_b32 s100, s96, 10
	s_add_u32 s100, s90, s100
	s_addc_u32 s101, s91, 0
	v_lshlrev_b32_e32 v255, 4, v255
	s_branch .Lp1b_issue

.Lp1b_skip:
	s_add_i32 s0, s0, 1
	s_mul_i32 s8, s0, s3
	s_mul_hi_u32 s9, s0, s33
	s_add_i32 s9, s9, s8
	s_mul_i32 s8, s0, s33
	v_mfma_f32_16x16x32_bf16 v[112:115], v[134:137], v[222:225], 0
	v_mfma_f32_16x16x32_bf16 v[112:115], v[138:141], v[230:233], v[112:115]
	s_add_u32 s26, s8, s2
	s_addc_u32 s27, s9, s73
	v_cmp_lt_i64_e64 s[8:9], s[26:27], v[170:171]
	s_ashr_i32 s24, s26, 31
	s_lshr_b32 s24, s24, 29
	v_mfma_f32_16x16x32_bf16 v[96:99], v[134:137], v[234:237], 0
	v_mfma_f32_16x16x32_bf16 v[96:99], v[138:141], v[242:245], v[96:99]
	s_add_i32 s24, s26, s24
	s_ashr_i32 s25, s24, 3
	s_and_b32 s24, s24, -8
	s_sub_i32 s24, s26, s24
	s_cmp_lt_i32 s24, 0
	v_mfma_f32_16x16x32_bf16 v[80:83], v[134:137], v[238:241], 0
	v_mfma_f32_16x16x32_bf16 v[80:83], v[138:141], v[246:249], v[80:83]
	s_movk_i32 s26, 0xb1
	s_cselect_b32 s26, s26, 0xb0
	s_mul_i32 s24, s24, s26
	s_add_i32 s24, s24, s25
	s_mul_hi_i32 s25, s24, 0x2e8ba2e9
	v_mfma_f32_16x16x32_bf16 v[76:79], v[142:145], v[238:241], 0
	v_mfma_f32_16x16x32_bf16 v[76:79], v[146:149], v[246:249], v[76:79]
	s_lshr_b32 s26, s25, 31
	s_ashr_i32 s25, s25, 5
	s_add_i32 s25, s25, s26
	s_lshl_b32 s26, s25, 3
	s_sub_i32 s27, 64, s26
	v_mfma_f32_16x16x32_bf16 v[92:95], v[142:145], v[234:237], 0
	v_mfma_f32_16x16x32_bf16 v[92:95], v[146:149], v[242:245], v[92:95]
	s_min_i32 s27, s27, 8
	s_abs_i32 s28, s27
	v_cvt_f32_u32_e32 v255, s28
	s_sub_i32 s34, 0, s28
	s_mulk_i32 s25, 0xb0
	v_mfma_f32_16x16x32_bf16 v[108:111], v[142:145], v[222:225], 0
	v_mfma_f32_16x16x32_bf16 v[108:111], v[146:149], v[230:233], v[108:111]
	s_sub_i32 s24, s24, s25
	v_rcp_iflag_f32_e32 v255, v255
	s_abs_i32 s25, s24
	s_xor_b32 s29, s24, s27
	s_ashr_i32 s29, s29, 31
	v_mfma_f32_16x16x32_bf16 v[124:127], v[142:145], v[218:221], 0
	v_mfma_f32_16x16x32_bf16 v[124:127], v[146:149], v[226:229], v[124:127]
	v_mul_f32_e32 v255, 0x4f7ffffe, v255
	v_cvt_u32_f32_e32 v255, v255
	s_nop 0
	v_readfirstlane_b32 s35, v255
	s_mul_i32 s34, s34, s35
	v_mfma_f32_16x16x32_bf16 v[120:123], v[150:153], v[218:221], 0
	v_mfma_f32_16x16x32_bf16 v[120:123], v[174:177], v[226:229], v[120:123]
	s_mul_hi_u32 s34, s35, s34
	s_add_i32 s35, s35, s34
	s_mul_hi_u32 s34, s25, s35
	s_mul_i32 s35, s34, s28
	s_sub_i32 s25, s25, s35
	v_mfma_f32_16x16x32_bf16 v[104:107], v[150:153], v[222:225], 0
	v_mfma_f32_16x16x32_bf16 v[104:107], v[174:177], v[230:233], v[104:107]
	s_add_i32 s38, s34, 1
	s_sub_i32 s35, s25, s28
	s_cmp_ge_u32 s25, s28
	s_cselect_b32 s34, s38, s34
	s_cselect_b32 s25, s35, s25
	v_mfma_f32_16x16x32_bf16 v[88:91], v[150:153], v[234:237], 0
	v_mfma_f32_16x16x32_bf16 v[88:91], v[174:177], v[242:245], v[88:91]
	s_add_i32 s35, s34, 1
	s_cmp_ge_u32 s25, s28
	s_cselect_b32 s25, s35, s34
	s_xor_b32 s25, s25, s29
	s_sub_i32 s28, s25, s29
	v_mfma_f32_16x16x32_bf16 v[72:75], v[150:153], v[238:241], 0
	v_mfma_f32_16x16x32_bf16 v[72:75], v[174:177], v[246:249], v[72:75]
	s_mul_i32 s25, s28, s27
	s_sub_i32 s24, s24, s25
	s_add_i32 s66, s26, s24
	s_mov_b32 s100, s66
	s_ashr_i32 s101, s66, 31
	v_mfma_f32_16x16x32_bf16 v[68:71], v[178:181], v[238:241], 0
	v_mfma_f32_16x16x32_bf16 v[68:71], v[182:185], v[246:249], v[68:71]
	s_lshl_b64 s[26:27], s[100:101], 19
	s_add_u32 s26, s40, s26
	s_addc_u32 s27, s41, s27
	s_and_b64 s[34:35], s[8:9], exec
	s_cselect_b32 s34, s27, s5
	v_mfma_f32_16x16x32_bf16 v[84:87], v[178:181], v[234:237], 0
	v_mfma_f32_16x16x32_bf16 v[84:87], v[182:185], v[242:245], v[84:87]
	s_cselect_b32 s35, s26, s4
	s_ashr_i32 s29, s28, 31
	s_lshl_b64 s[100:101], s[28:29], 19
	s_add_u32 s62, s10, s100
	s_addc_u32 s63, s11, s101
	v_mfma_f32_16x16x32_bf16 v[100:103], v[178:181], v[222:225], 0
	v_mfma_f32_16x16x32_bf16 v[100:103], v[182:185], v[230:233], v[100:103]
	s_and_b64 s[100:101], s[8:9], exec
	s_cselect_b32 s29, s63, s83
	s_cselect_b32 s38, s62, s82
	v_mfma_f32_16x16x32_bf16 v[116:119], v[178:181], v[218:221], 0
	v_mfma_f32_16x16x32_bf16 v[116:119], v[182:185], v[226:229], v[116:119]
	s_barrier
	s_add_i32 s24, s1, s77
	v_lshl_add_u64 v[154:155], s[86:87], 0, v[158:159]
	s_mov_b32 m0, s24
	ds_read_b128 v[218:221], v207 offset:16384
	ds_read_b128 v[222:225], v207 offset:18432
	ds_read_b128 v[226:229], v208 offset:16384
	ds_read_b128 v[230:233], v208 offset:18432
	ds_read_b128 v[234:237], v207 offset:20480
	ds_read_b128 v[238:241], v207 offset:22528
	ds_read_b128 v[242:245], v208 offset:20480
	ds_read_b128 v[246:249], v208 offset:22528
	global_load_lds_dwordx4 v[154:155], off
	v_lshl_add_u64 v[250:251], v[154:155], 0, s[14:15]
	s_add_i32 m0, s24, 0x2000
	s_add_i32 s24, s12, s77
	global_load_lds_dwordx4 v[250:251], off
	v_lshl_add_u64 v[250:251], v[154:155], 0, s[16:17]
	s_mov_b32 m0, s24
	s_nop 0
	global_load_lds_dwordx4 v[250:251], off
	v_lshl_add_u64 v[250:251], v[154:155], 0, s[18:19]
	s_add_i32 m0, s24, 0x2000
	s_nop 0
	global_load_lds_dwordx4 v[250:251], off
	s_waitcnt vmcnt(4)
	s_waitcnt lgkmcnt(0)
	s_barrier
	v_mfma_f32_16x16x32_bf16 v[64:67], v[134:137], v[218:221], 0
	v_mfma_f32_16x16x32_bf16 v[64:67], v[138:141], v[226:229], v[64:67]
	v_mfma_f32_16x16x32_bf16 v[48:51], v[134:137], v[222:225], 0
	v_mfma_f32_16x16x32_bf16 v[48:51], v[138:141], v[230:233], v[48:51]
	v_mfma_f32_16x16x32_bf16 v[32:35], v[134:137], v[234:237], 0
	v_mfma_f32_16x16x32_bf16 v[32:35], v[138:141], v[242:245], v[32:35]
	v_mfma_f32_16x16x32_bf16 v[16:19], v[134:137], v[238:241], 0
	v_mfma_f32_16x16x32_bf16 v[16:19], v[138:141], v[246:249], v[16:19]
	v_mfma_f32_16x16x32_bf16 v[12:15], v[142:145], v[238:241], 0
	v_mfma_f32_16x16x32_bf16 v[12:15], v[146:149], v[246:249], v[12:15]
	v_mfma_f32_16x16x32_bf16 v[28:31], v[142:145], v[234:237], 0
	v_mfma_f32_16x16x32_bf16 v[28:31], v[146:149], v[242:245], v[28:31]
	v_mfma_f32_16x16x32_bf16 v[44:47], v[142:145], v[222:225], 0
	v_mfma_f32_16x16x32_bf16 v[44:47], v[146:149], v[230:233], v[44:47]
	v_mfma_f32_16x16x32_bf16 v[60:63], v[142:145], v[218:221], 0
	v_mfma_f32_16x16x32_bf16 v[60:63], v[146:149], v[226:229], v[60:63]
	v_mfma_f32_16x16x32_bf16 v[56:59], v[150:153], v[218:221], 0
	v_mfma_f32_16x16x32_bf16 v[56:59], v[174:177], v[226:229], v[56:59]
	v_mfma_f32_16x16x32_bf16 v[40:43], v[150:153], v[222:225], 0
	v_mfma_f32_16x16x32_bf16 v[40:43], v[174:177], v[230:233], v[40:43]
	v_mfma_f32_16x16x32_bf16 v[24:27], v[150:153], v[234:237], 0
	v_mfma_f32_16x16x32_bf16 v[24:27], v[174:177], v[242:245], v[24:27]
	v_mfma_f32_16x16x32_bf16 v[8:11], v[150:153], v[238:241], 0
	v_mfma_f32_16x16x32_bf16 v[8:11], v[174:177], v[246:249], v[8:11]
	v_mfma_f32_16x16x32_bf16 v[4:7], v[178:181], v[238:241], 0
	v_mfma_f32_16x16x32_bf16 v[4:7], v[182:185], v[246:249], v[4:7]
	v_mfma_f32_16x16x32_bf16 v[20:23], v[178:181], v[234:237], 0
	v_mfma_f32_16x16x32_bf16 v[20:23], v[182:185], v[242:245], v[20:23]
	v_mfma_f32_16x16x32_bf16 v[36:39], v[178:181], v[222:225], 0
	v_mfma_f32_16x16x32_bf16 v[36:39], v[182:185], v[230:233], v[36:39]
	v_mfma_f32_16x16x32_bf16 v[52:55], v[178:181], v[218:221], 0
	v_mfma_f32_16x16x32_bf16 v[52:55], v[182:185], v[226:229], v[52:55]
	s_barrier
	ds_read_b128 v[134:137], v213
	ds_read_b128 v[138:141], v214
	ds_read_b128 v[142:145], v209
	ds_read_b128 v[146:149], v210
	ds_read_b128 v[150:153], v215
	ds_read_b128 v[174:177], v216
	ds_read_b128 v[178:181], v211
	ds_read_b128 v[182:185], v212
	s_mov_b32 m0, s79
	v_lshl_add_u64 v[250:251], s[82:83], 0, v[0:1]
	ds_read_b128 v[218:221], v207 offset:32768
	ds_read_b128 v[222:225], v207 offset:34816
	ds_read_b128 v[226:229], v208 offset:32768
	ds_read_b128 v[230:233], v208 offset:34816
	ds_read_b128 v[234:237], v207 offset:36864
	ds_read_b128 v[238:241], v207 offset:38912
	ds_read_b128 v[242:245], v208 offset:36864
	ds_read_b128 v[246:249], v208 offset:38912
	global_load_lds_dwordx4 v[250:251], off
	v_lshl_add_u64 v[252:253], v[250:251], 0, s[20:21]
	s_mov_b32 m0, s81
	s_nop 0
	global_load_lds_dwordx4 v[252:253], off
	v_lshl_add_u64 v[252:253], v[250:251], 0, s[14:15]
	s_mov_b32 m0, s97
	v_lshl_add_u64 v[250:251], v[250:251], 0, s[22:23]
	global_load_lds_dwordx4 v[252:253], off
	s_mov_b32 m0, s64
	s_nop 0
	global_load_lds_dwordx4 v[250:251], off
	s_waitcnt vmcnt(8)
	s_waitcnt lgkmcnt(0)
	s_barrier
	v_mfma_f32_16x16x32_bf16 v[128:131], v[134:137], v[218:221], v[128:131]
	v_mfma_f32_16x16x32_bf16 v[128:131], v[138:141], v[226:229], v[128:131]
	v_mfma_f32_16x16x32_bf16 v[112:115], v[138:141], v[230:233], v[112:115]
	v_mfma_f32_16x16x32_bf16 v[112:115], v[134:137], v[222:225], v[112:115]
	v_mfma_f32_16x16x32_bf16 v[96:99], v[134:137], v[234:237], v[96:99]
	v_mfma_f32_16x16x32_bf16 v[96:99], v[138:141], v[242:245], v[96:99]
	v_mfma_f32_16x16x32_bf16 v[80:83], v[138:141], v[246:249], v[80:83]
	v_mfma_f32_16x16x32_bf16 v[80:83], v[134:137], v[238:241], v[80:83]
	v_mfma_f32_16x16x32_bf16 v[76:79], v[142:145], v[238:241], v[76:79]
	v_mfma_f32_16x16x32_bf16 v[76:79], v[146:149], v[246:249], v[76:79]
	v_mfma_f32_16x16x32_bf16 v[92:95], v[146:149], v[242:245], v[92:95]
	v_mfma_f32_16x16x32_bf16 v[92:95], v[142:145], v[234:237], v[92:95]
	v_mfma_f32_16x16x32_bf16 v[108:111], v[142:145], v[222:225], v[108:111]
	v_mfma_f32_16x16x32_bf16 v[108:111], v[146:149], v[230:233], v[108:111]
	v_mfma_f32_16x16x32_bf16 v[124:127], v[146:149], v[226:229], v[124:127]
	v_mfma_f32_16x16x32_bf16 v[124:127], v[142:145], v[218:221], v[124:127]
	v_mfma_f32_16x16x32_bf16 v[120:123], v[150:153], v[218:221], v[120:123]
	v_mfma_f32_16x16x32_bf16 v[120:123], v[174:177], v[226:229], v[120:123]
	v_mfma_f32_16x16x32_bf16 v[104:107], v[174:177], v[230:233], v[104:107]
	v_mfma_f32_16x16x32_bf16 v[104:107], v[150:153], v[222:225], v[104:107]
	v_mfma_f32_16x16x32_bf16 v[88:91], v[150:153], v[234:237], v[88:91]
	v_mfma_f32_16x16x32_bf16 v[88:91], v[174:177], v[242:245], v[88:91]
	v_mfma_f32_16x16x32_bf16 v[72:75], v[174:177], v[246:249], v[72:75]
	v_mfma_f32_16x16x32_bf16 v[72:75], v[150:153], v[238:241], v[72:75]
	v_mfma_f32_16x16x32_bf16 v[68:71], v[178:181], v[238:241], v[68:71]
	v_mfma_f32_16x16x32_bf16 v[68:71], v[182:185], v[246:249], v[68:71]
	v_mfma_f32_16x16x32_bf16 v[84:87], v[182:185], v[242:245], v[84:87]
	v_mfma_f32_16x16x32_bf16 v[84:87], v[178:181], v[234:237], v[84:87]
	v_mfma_f32_16x16x32_bf16 v[100:103], v[178:181], v[222:225], v[100:103]
	v_mfma_f32_16x16x32_bf16 v[100:103], v[182:185], v[230:233], v[100:103]
	v_mfma_f32_16x16x32_bf16 v[116:119], v[182:185], v[226:229], v[116:119]
	v_mfma_f32_16x16x32_bf16 v[116:119], v[178:181], v[218:221], v[116:119]
	s_barrier
	s_add_i32 s24, s70, s77
	v_lshl_add_u64 v[250:251], v[154:155], 0, s[48:49]
	s_mov_b32 m0, s24
	ds_read_b128 v[218:221], v207 offset:49152
	ds_read_b128 v[222:225], v207 offset:51200
	ds_read_b128 v[226:229], v208 offset:49152
	ds_read_b128 v[230:233], v208 offset:51200
	ds_read_b128 v[234:237], v207 offset:53248
	ds_read_b128 v[238:241], v207 offset:55296
	ds_read_b128 v[242:245], v208 offset:53248
	ds_read_b128 v[246:249], v208 offset:55296
	global_load_lds_dwordx4 v[250:251], off
	v_lshl_add_u64 v[250:251], v[154:155], 0, s[50:51]
	s_add_i32 m0, s24, 0x2000
	s_add_i32 s24, s71, s77
	global_load_lds_dwordx4 v[250:251], off
	v_lshl_add_u64 v[250:251], v[154:155], 0, s[52:53]
	s_mov_b32 m0, s24
	v_lshl_add_u64 v[154:155], v[154:155], 0, s[54:55]
	global_load_lds_dwordx4 v[250:251], off
	s_add_i32 m0, s24, 0x2000
	s_nop 0
	global_load_lds_dwordx4 v[154:155], off
	s_waitcnt vmcnt(4)
	s_waitcnt lgkmcnt(0)
	s_barrier
	v_mfma_f32_16x16x32_bf16 v[64:67], v[134:137], v[218:221], v[64:67]
	v_mfma_f32_16x16x32_bf16 v[64:67], v[138:141], v[226:229], v[64:67]
	v_mfma_f32_16x16x32_bf16 v[48:51], v[138:141], v[230:233], v[48:51]
	v_mfma_f32_16x16x32_bf16 v[48:51], v[134:137], v[222:225], v[48:51]
	v_mfma_f32_16x16x32_bf16 v[32:35], v[134:137], v[234:237], v[32:35]
	v_mfma_f32_16x16x32_bf16 v[32:35], v[138:141], v[242:245], v[32:35]
	v_mfma_f32_16x16x32_bf16 v[16:19], v[138:141], v[246:249], v[16:19]
	v_mfma_f32_16x16x32_bf16 v[16:19], v[134:137], v[238:241], v[16:19]
	v_mfma_f32_16x16x32_bf16 v[12:15], v[142:145], v[238:241], v[12:15]
	v_mfma_f32_16x16x32_bf16 v[12:15], v[146:149], v[246:249], v[12:15]
	v_mfma_f32_16x16x32_bf16 v[28:31], v[146:149], v[242:245], v[28:31]
	v_mfma_f32_16x16x32_bf16 v[28:31], v[142:145], v[234:237], v[28:31]
	v_mfma_f32_16x16x32_bf16 v[44:47], v[142:145], v[222:225], v[44:47]
	v_mfma_f32_16x16x32_bf16 v[44:47], v[146:149], v[230:233], v[44:47]
	v_mfma_f32_16x16x32_bf16 v[60:63], v[146:149], v[226:229], v[60:63]
	v_mfma_f32_16x16x32_bf16 v[60:63], v[142:145], v[218:221], v[60:63]
	v_mfma_f32_16x16x32_bf16 v[56:59], v[150:153], v[218:221], v[56:59]
	v_mfma_f32_16x16x32_bf16 v[56:59], v[174:177], v[226:229], v[56:59]
	v_mfma_f32_16x16x32_bf16 v[40:43], v[174:177], v[230:233], v[40:43]
	v_mfma_f32_16x16x32_bf16 v[40:43], v[150:153], v[222:225], v[40:43]
	v_mfma_f32_16x16x32_bf16 v[24:27], v[150:153], v[234:237], v[24:27]
	v_mfma_f32_16x16x32_bf16 v[24:27], v[174:177], v[242:245], v[24:27]
	v_mfma_f32_16x16x32_bf16 v[8:11], v[174:177], v[246:249], v[8:11]
	v_mfma_f32_16x16x32_bf16 v[8:11], v[150:153], v[238:241], v[8:11]
	v_mfma_f32_16x16x32_bf16 v[4:7], v[178:181], v[238:241], v[4:7]
	v_mfma_f32_16x16x32_bf16 v[4:7], v[182:185], v[246:249], v[4:7]
	v_mfma_f32_16x16x32_bf16 v[20:23], v[182:185], v[242:245], v[20:23]
	v_mfma_f32_16x16x32_bf16 v[20:23], v[178:181], v[234:237], v[20:23]
	v_mfma_f32_16x16x32_bf16 v[36:39], v[178:181], v[222:225], v[36:39]
	v_mfma_f32_16x16x32_bf16 v[36:39], v[182:185], v[230:233], v[36:39]
	v_mfma_f32_16x16x32_bf16 v[52:55], v[182:185], v[226:229], v[52:55]
	v_mfma_f32_16x16x32_bf16 v[52:55], v[178:181], v[218:221], v[52:55]
	s_barrier
	s_add_i32 s94, s94, 2
	s_add_u32 vcc_lo, vcc_lo, 0x100
	s_addc_u32 vcc_hi, vcc_hi, 0
	s_cmp_gt_u32 s94, 13
